# W2in copy moved from the mixer-GEMM tail (where it overran the last unit) into P0 on the adaLN workgroups after their item; P5 tail copies only Wout
# baseline (speedup 1.0000x reference)
.LBB0_35:
	s_cmpk_lg_i32 s78, 0x100
	s_cbranch_scc1 .Lp0w_orig
	v_lshrrev_b32_e32 v1, 6, v236
	v_and_b32_e32 v2, 63, v236
	v_readfirstlane_b32 s0, v1
	v_and_b32_e32 v3, 31, v2
	v_lshrrev_b32_e32 v4, 5, v2
	s_nop 3
	s_lshl_b32 s2, s0, 14
	v_bfe_u32 v5, v3, 2, 1
	v_xor_b32_e32 v5, v5, v4
	v_lshlrev_b32_e32 v5, 6, v5
	v_lshl_or_b32 v5, v3, 9, v5
	v_add_u32_e32 v5, s2, v5
	v_and_b32_e32 v6, 3, v3
	v_xor_b32_e32 v7, 0, v6
	v_lshl_add_u32 v7, v7, 4, v5
	v_xor_b32_e32 v8, 1, v6
	v_lshl_add_u32 v8, v8, 4, v5
	v_xor_b32_e32 v9, 2, v6
	v_lshl_add_u32 v9, v9, 4, v5
	v_xor_b32_e32 v10, 3, v6
	v_lshl_add_u32 v10, v10, 4, v5
	v_and_b32_e32 v11, 7, v2
	v_xor_b32_e32 v11, v11, v4
	v_lshrrev_b32_e32 v12, 3, v2
	v_lshlrev_b32_e32 v12, 7, v12
	v_add_u32_e32 v12, s2, v12
	v_xor_b32_e32 v13, 0, v11
	v_lshl_add_u32 v13, v13, 4, v12
	v_xor_b32_e32 v14, 2, v11
	v_lshl_add_u32 v14, v14, 4, v12
	v_xor_b32_e32 v15, 4, v11
	v_lshl_add_u32 v15, v15, 4, v12
	v_xor_b32_e32 v16, 6, v11
	v_lshl_add_u32 v16, v16, 4, v12
	v_lshrrev_b32_e32 v17, 3, v2
	v_lshlrev_b32_e32 v17, 11, v17
	v_and_b32_e32 v18, 7, v2
	v_lshl_or_b32 v17, v18, 4, v17
	s_mov_b32 s24, 0
	s_mov_b32 s3, 0
	s_cmpk_lt_i32 s97, 0x90
	s_cbranch_scc0 .Lp0w_nonada
	s_mul_i32 s1, s0, 0x90
	s_add_i32 s1, s1, s97
	s_mov_b32 s24, 1
	s_mov_b32 s3, 1
	s_cmpk_ge_u32 s1, 0x2c0
	s_cbranch_scc1 .Lp0w_done
	s_branch .Lp0w_round
.Lp0w_nonada:
	s_sub_i32 s1, s97, 0x90
	s_lshl_b32 s1, s1, 3
	s_add_i32 s1, s1, s0
.Lp0w_round:
	s_cmpk_ge_u32 s1, 0x6e0
	s_cbranch_scc1 .Lp0w_done
	s_movk_i32 s9, 0x80
	s_cmpk_lt_u32 s1, 0x2c0
	s_cbranch_scc0 .Lp0w_win
	s_mul_i32 s4, s1, 0x5d2
	s_lshr_b32 s4, s4, 16
	s_mul_i32 s5, s4, 44
	s_sub_i32 s5, s1, s5
	s_and_b32 s6, s5, 1
	s_mul_i32 s6, s6, 0xb00
	s_lshr_b32 s7, s5, 1
	s_lshl_b32 s7, s7, 7
	s_add_i32 s6, s6, s7
	s_movk_i32 s8, 0x1600
	v_readlane_b32 s18, v246, 7
	v_readlane_b32 s19, v246, 8
	s_add_u32 s12, s74, 0x100000
	s_addc_u32 s13, s75, 0
	s_cmp_eq_u32 s24, 0
	s_cbranch_scc1 .Lp0w_go
	s_mov_b32 s18, s66
	s_mov_b32 s19, s67
	s_add_u32 s12, s74, 0x2500000
	s_addc_u32 s13, s75, 0
	s_branch .Lp0w_go

.LBB0_700:
	v_readlane_b32 s4, v246, 17
	s_cmpk_lt_i32 s96, 0xc4
	v_readlane_b32 s5, v246, 18
	s_cselect_b64 s[2:3], -1, 0
	s_xor_b64 s[4:5], s[4:5], -1
	s_or_b64 s[2:3], s[2:3], s[4:5]
	s_and_b64 vcc, exec, s[2:3]
	s_cbranch_vccnz .LBB0_713
	s_lshl_b32 s2, s96, 3
	s_addk_i32 s2, 0xf9e0
	v_add_u32_e32 v0, s2, v209
	s_movk_i32 s2, 0x200
	v_cmp_gt_u32_e32 vcc, s2, v0
	s_and_saveexec_b64 s[2:3], vcc
	s_cbranch_execz .LBB0_712
	v_add_u32_e32 v17, 0x2c00, v0
	v_lshlrev_b32_e32 v0, 8, v236
	v_and_b32_e32 v0, 0x3c000, v0
	v_add_u32_e32 v1, 0, v0
	v_and_b32_e32 v0, 31, v236
	v_lshrrev_b32_e32 v16, 5, v208
	v_lshlrev_b32_e32 v0, 2, v0
	v_mul_u32_u24_e32 v2, 0x84, v16
	v_add3_u32 v18, v1, v0, v2
	v_lshlrev_b32_e32 v2, 3, v236
	v_lshrrev_b32_e32 v19, 3, v208
	v_and_b32_e32 v8, 56, v2
	v_mul_u32_u24_e32 v2, 0x84, v8
	v_lshlrev_b32_e32 v3, 2, v19
	v_readlane_b32 s4, v246, 1
	v_add3_u32 v20, v1, v2, v3
	v_mov_b32_e32 v1, 0
	v_readlane_b32 s12, v246, 9
	v_readlane_b32 s13, v246, 10
	v_lshl_add_u64 v[2:3], s[62:63], 0, v[0:1]
	v_lshl_add_u64 v[4:5], s[66:67], 0, v[0:1]
	v_readlane_b32 s5, v246, 2
	v_lshl_add_u64 v[6:7], s[12:13], 0, v[0:1]
	v_lshlrev_b32_e32 v0, 1, v8
	v_lshl_add_u64 v[12:13], s[74:75], 0, v[0:1]
	s_mov_b64 s[4:5], 0x2300000
	v_lshl_add_u64 v[8:9], v[12:13], 0, s[4:5]
	s_mov_b64 s[4:5], 0x2500000
	v_readlane_b32 s10, v246, 7
	v_readlane_b32 s11, v246, 8
	v_readlane_b32 s14, v246, 11
	v_readlane_b32 s15, v246, 12
	v_readlane_b32 s16, v246, 13
	v_readlane_b32 s17, v246, 14
	v_readlane_b32 s18, v246, 15
	v_readlane_b32 s19, v246, 16
	v_lshl_add_u64 v[10:11], v[12:13], 0, s[4:5]
	s_mov_b64 s[4:5], 0xc00000
	v_or_b32_e32 v21, 8, v19
	v_or_b32_e32 v22, 16, v19
	v_or_b32_e32 v23, 24, v19
	v_lshl_add_u64 v[12:13], v[12:13], 0, s[4:5]
	v_lshlrev_b32_e32 v24, 5, v17
	v_lshlrev_b32_e32 v25, 1, v17
	s_mov_b64 s[4:5], 0
	s_movk_i32 s10, 0x20ff
	s_movk_i32 s11, 0x2bff
	s_movk_i32 s12, 0x60
	s_mov_b32 s13, 0xb000
	s_mov_b32 s14, 0x16000
	s_mov_b32 s15, 0x21000
	s_mov_b32 s16, 0x2c000
	s_mov_b32 s17, 0x37000
	s_mov_b32 s18, 0x42000
	s_mov_b32 s19, 0x4d000
	s_mov_b32 s20, 0x58000
	s_mov_b32 s21, 0x63000
	s_mov_b32 s22, 0x6e000
	s_mov_b32 s23, 0x79000
	s_mov_b32 s24, 0x84000
	s_mov_b32 s25, 0x8f000
	s_mov_b32 s26, 0x9a000
	s_mov_b32 s27, 0xa5000
	s_mov_b32 s28, 0xb0000
	s_mov_b32 s29, 0xbb000
	s_mov_b32 s30, 0xc6000
	s_mov_b32 s31, 0xd1000
	s_mov_b32 s33, 0xdc000
	s_mov_b32 s34, 0xe7000
	s_mov_b32 s35, 0xf2000
	s_mov_b32 s36, 0xfd000
	s_mov_b32 s37, 0x108000
	s_mov_b32 s38, 0x113000
	s_mov_b32 s39, 0x11e000
	s_mov_b32 s40, 0x129000
	s_mov_b32 s41, 0x134000
	s_mov_b32 s42, 0x13f000
	s_mov_b32 s43, 0x14a000
	s_mov_b32 s44, 0x155000
	s_movk_i32 s45, 0x2c1f
	v_add_u32_e32 v26, 0x400, v18
	v_add_u32_e32 v27, 0x800, v18
	v_add_u32_e32 v28, 0xc00, v18
	v_add_u32_e32 v29, 0x1000, v18
	v_add_u32_e32 v30, 0x1400, v18
	v_add_u32_e32 v31, 0x1800, v18
	v_add_u32_e32 v32, 0x1c00, v18
	v_readlane_b32 s6, v246, 3
	v_readlane_b32 s7, v246, 4
	v_readlane_b32 s8, v246, 5
	v_readlane_b32 s9, v246, 6
	s_branch .LBB0_704
